# GEMM K-loops: last two LDS-DMA issues of each 6-DMA load segment moved into the wave's own MFMA burst (vmcnt 8->6 there)
# speedup vs baseline: 1.0020x; 1.0020x over previous
.LBB0_348:
	s_add_i32 s12, s12, s11
	s_add_u32 s11, s44, s12
	s_addc_u32 s12, s45, 0
	s_add_u32 s10, s42, s10
	s_addc_u32 s13, s43, 0
	s_add_u32 s10, s10, 0x100
	s_addc_u32 s13, s13, 0
	s_add_i32 s14, 0, 0x10000
	s_and_b64 s[0:1], exec, s[0:1]
	v_add_u32_e32 v155, s14, v152
	s_cselect_b32 s1, s6, s13
	s_cselect_b32 s0, s7, s10
	s_add_i32 s13, 0, 0x14000
	ds_read_b128 v[140:143], v155
	ds_read_b128 v[148:151], v155 offset:1024
	ds_read_b128 v[156:159], v155 offset:2048
	ds_read_b128 v[160:163], v155 offset:3072
	v_add_u32_e32 v155, s13, v152
	ds_read_b128 v[164:167], v155
	ds_read_b128 v[168:171], v155 offset:1024
	ds_read_b128 v[172:175], v155 offset:2048
	ds_read_b128 v[176:179], v155 offset:3072
	s_add_u32 s10, s11, 0x140080
	s_addc_u32 s11, s12, 0
	s_add_i32 m0, s53, 0xc000
	ds_read_b128 v[180:183], v154
	ds_read_b128 v[184:187], v154 offset:1024
	ds_read_b128 v[188:191], v154 offset:2048
	ds_read_b128 v[192:195], v154 offset:3072
	ds_read_b128 v[196:199], v154 offset:4096
	ds_read_b128 v[200:203], v154 offset:5120
	ds_read_b128 v[204:207], v154 offset:6144
	ds_read_b128 v[208:211], v154 offset:7168
	global_load_lds_dwordx4 v146, s[10:11]
	s_add_i32 m0, s53, 0xe000
	s_nop 0
	global_load_lds_dwordx4 v136, s[10:11]
	s_waitcnt vmcnt(8)
	s_waitcnt lgkmcnt(0)
	s_barrier
	s_setprio 1
	s_waitcnt lgkmcnt(0)
	v_mfma_f32_16x16x32_bf16 v[122:125], v[140:143], v[180:183], v[122:125]
	v_mfma_f32_16x16x32_bf16 v[114:117], v[156:159], v[180:183], v[114:117]
	v_mfma_f32_16x16x32_bf16 v[102:105], v[140:143], v[188:191], v[102:105]
	v_mfma_f32_16x16x32_bf16 v[78:81], v[156:159], v[188:191], v[78:81]
	v_mfma_f32_16x16x32_bf16 v[70:73], v[140:143], v[196:199], v[70:73]
	v_mfma_f32_16x16x32_bf16 v[50:53], v[156:159], v[196:199], v[50:53]
	v_mfma_f32_16x16x32_bf16 v[42:45], v[140:143], v[204:207], v[42:45]
	v_mfma_f32_16x16x32_bf16 v[26:29], v[156:159], v[204:207], v[26:29]
	v_mfma_f32_16x16x32_bf16 v[122:125], v[148:151], v[184:187], v[122:125]
	v_mfma_f32_16x16x32_bf16 v[114:117], v[160:163], v[184:187], v[114:117]
	v_mfma_f32_16x16x32_bf16 v[102:105], v[148:151], v[192:195], v[102:105]
	v_mfma_f32_16x16x32_bf16 v[78:81], v[160:163], v[192:195], v[78:81]
	v_mfma_f32_16x16x32_bf16 v[70:73], v[148:151], v[200:203], v[70:73]
	v_mfma_f32_16x16x32_bf16 v[50:53], v[160:163], v[200:203], v[50:53]
	v_mfma_f32_16x16x32_bf16 v[42:45], v[148:151], v[208:211], v[42:45]
	v_mfma_f32_16x16x32_bf16 v[26:29], v[160:163], v[208:211], v[26:29]
	s_setprio 0
	s_setprio 1
	v_mfma_f32_16x16x32_bf16 v[126:129], v[164:167], v[180:183], v[126:129]
	v_mfma_f32_16x16x32_bf16 v[130:133], v[172:175], v[180:183], v[130:133]
	v_mfma_f32_16x16x32_bf16 v[110:113], v[164:167], v[188:191], v[110:113]
	v_mfma_f32_16x16x32_bf16 v[118:121], v[172:175], v[188:191], v[118:121]
	v_mfma_f32_16x16x32_bf16 v[86:89], v[164:167], v[196:199], v[86:89]
	v_mfma_f32_16x16x32_bf16 v[90:93], v[172:175], v[196:199], v[90:93]
	v_mfma_f32_16x16x32_bf16 v[58:61], v[164:167], v[204:207], v[58:61]
	v_mfma_f32_16x16x32_bf16 v[94:97], v[172:175], v[204:207], v[94:97]
	v_mfma_f32_16x16x32_bf16 v[126:129], v[168:171], v[184:187], v[126:129]
	v_mfma_f32_16x16x32_bf16 v[130:133], v[176:179], v[184:187], v[130:133]
	v_mfma_f32_16x16x32_bf16 v[110:113], v[168:171], v[192:195], v[110:113]
	v_mfma_f32_16x16x32_bf16 v[118:121], v[176:179], v[192:195], v[118:121]
	v_mfma_f32_16x16x32_bf16 v[86:89], v[168:171], v[200:203], v[86:89]
	v_mfma_f32_16x16x32_bf16 v[90:93], v[176:179], v[200:203], v[90:93]
	v_mfma_f32_16x16x32_bf16 v[58:61], v[168:171], v[208:211], v[58:61]
	v_mfma_f32_16x16x32_bf16 v[94:97], v[176:179], v[208:211], v[94:97]
	s_setprio 0
	s_barrier
	s_add_i32 s10, s14, s52
	s_mov_b32 m0, s10
	ds_read_b128 v[180:183], v154 offset:16384
	ds_read_b128 v[184:187], v154 offset:17408
	ds_read_b128 v[188:191], v154 offset:18432
	ds_read_b128 v[192:195], v154 offset:19456
	ds_read_b128 v[196:199], v154 offset:20480
	ds_read_b128 v[200:203], v154 offset:21504
	ds_read_b128 v[204:207], v154 offset:22528
	ds_read_b128 v[208:211], v154 offset:23552
	global_load_lds_dwordx4 v138, s[0:1]
	s_add_i32 m0, s10, 0x2000
	s_add_u32 s10, s0, 0x80000
	s_addc_u32 s11, s1, 0
	s_add_i32 s12, s13, s52
	global_load_lds_dwordx4 v134, s[0:1]
	s_mov_b32 m0, s12
	s_nop 0
	global_load_lds_dwordx4 v138, s[10:11]
	s_add_i32 m0, s12, 0x2000
	s_nop 0
	global_load_lds_dwordx4 v134, s[10:11]
	s_waitcnt vmcnt(6)
	s_waitcnt lgkmcnt(0)
	s_barrier
	s_setprio 1
	s_waitcnt lgkmcnt(0)
	v_mfma_f32_16x16x32_bf16 v[82:85], v[140:143], v[180:183], v[82:85]
	v_mfma_f32_16x16x32_bf16 v[62:65], v[156:159], v[180:183], v[62:65]
	v_mfma_f32_16x16x32_bf16 v[54:57], v[140:143], v[188:191], v[54:57]
	v_mfma_f32_16x16x32_bf16 v[34:37], v[156:159], v[188:191], v[34:37]
	v_mfma_f32_16x16x32_bf16 v[30:33], v[140:143], v[196:199], v[30:33]
	v_mfma_f32_16x16x32_bf16 v[14:17], v[156:159], v[196:199], v[14:17]
	v_mfma_f32_16x16x32_bf16 v[10:13], v[140:143], v[204:207], v[10:13]
	s_mov_b32 m0, s53
	v_mfma_f32_16x16x32_bf16 v[6:9], v[156:159], v[204:207], v[6:9]
	global_load_lds_dwordx4 v146, s[46:47]
	v_mfma_f32_16x16x32_bf16 v[82:85], v[148:151], v[184:187], v[82:85]
	v_mfma_f32_16x16x32_bf16 v[62:65], v[160:163], v[184:187], v[62:65]
	v_mfma_f32_16x16x32_bf16 v[54:57], v[148:151], v[192:195], v[54:57]
	v_mfma_f32_16x16x32_bf16 v[34:37], v[160:163], v[192:195], v[34:37]
	v_mfma_f32_16x16x32_bf16 v[30:33], v[148:151], v[200:203], v[30:33]
	v_mfma_f32_16x16x32_bf16 v[14:17], v[160:163], v[200:203], v[14:17]
	v_mfma_f32_16x16x32_bf16 v[10:13], v[148:151], v[208:211], v[10:13]
	s_mov_b32 m0, s54
	v_mfma_f32_16x16x32_bf16 v[6:9], v[160:163], v[208:211], v[6:9]
	global_load_lds_dwordx4 v136, s[46:47]
	s_setprio 0
	s_setprio 1
	v_mfma_f32_16x16x32_bf16 v[98:101], v[164:167], v[180:183], v[98:101]
	v_mfma_f32_16x16x32_bf16 v[106:109], v[172:175], v[180:183], v[106:109]
	v_mfma_f32_16x16x32_bf16 v[66:69], v[164:167], v[188:191], v[66:69]
	v_mfma_f32_16x16x32_bf16 v[74:77], v[172:175], v[188:191], v[74:77]
	v_mfma_f32_16x16x32_bf16 v[38:41], v[164:167], v[196:199], v[38:41]
	v_mfma_f32_16x16x32_bf16 v[46:49], v[172:175], v[196:199], v[46:49]
	v_mfma_f32_16x16x32_bf16 v[18:21], v[164:167], v[204:207], v[18:21]
	v_mfma_f32_16x16x32_bf16 v[22:25], v[172:175], v[204:207], v[22:25]
	v_mfma_f32_16x16x32_bf16 v[98:101], v[168:171], v[184:187], v[98:101]
	v_mfma_f32_16x16x32_bf16 v[106:109], v[176:179], v[184:187], v[106:109]
	v_mfma_f32_16x16x32_bf16 v[66:69], v[168:171], v[192:195], v[66:69]
	v_mfma_f32_16x16x32_bf16 v[74:77], v[176:179], v[192:195], v[74:77]
	v_mfma_f32_16x16x32_bf16 v[38:41], v[168:171], v[200:203], v[38:41]
	v_mfma_f32_16x16x32_bf16 v[46:49], v[176:179], v[200:203], v[46:49]
	v_mfma_f32_16x16x32_bf16 v[18:21], v[168:171], v[208:211], v[18:21]
	v_mfma_f32_16x16x32_bf16 v[22:25], v[176:179], v[208:211], v[22:25]
	s_setprio 0
	s_barrier
	s_add_i32 s12, 0, 0x18000
	v_add_u32_e32 v155, s12, v152
	s_add_i32 s13, 0, 0x1c000
	ds_read_b128 v[140:143], v155
	ds_read_b128 v[148:151], v155 offset:1024
	ds_read_b128 v[156:159], v155 offset:2048
	ds_read_b128 v[160:163], v155 offset:3072
	v_add_u32_e32 v155, s13, v152
	ds_read_b128 v[164:167], v155
	ds_read_b128 v[168:171], v155 offset:1024
	ds_read_b128 v[172:175], v155 offset:2048
	ds_read_b128 v[176:179], v155 offset:3072
	s_add_u32 s10, s46, 0x140000
	s_addc_u32 s11, s47, 0
	s_mov_b32 m0, s55
	ds_read_b128 v[180:183], v154 offset:32768
	ds_read_b128 v[184:187], v154 offset:33792
	ds_read_b128 v[188:191], v154 offset:34816
	ds_read_b128 v[192:195], v154 offset:35840
	ds_read_b128 v[196:199], v154 offset:36864
	ds_read_b128 v[200:203], v154 offset:37888
	ds_read_b128 v[204:207], v154 offset:38912
	ds_read_b128 v[208:211], v154 offset:39936
	global_load_lds_dwordx4 v146, s[10:11]
	s_mov_b32 m0, s56
	s_nop 0
	global_load_lds_dwordx4 v136, s[10:11]
	s_waitcnt vmcnt(8)
	s_waitcnt lgkmcnt(0)
	s_barrier
	s_setprio 1
	s_waitcnt lgkmcnt(0)
	v_mfma_f32_16x16x32_bf16 v[122:125], v[140:143], v[180:183], v[122:125]
	v_mfma_f32_16x16x32_bf16 v[114:117], v[156:159], v[180:183], v[114:117]
	v_mfma_f32_16x16x32_bf16 v[102:105], v[140:143], v[188:191], v[102:105]
	v_mfma_f32_16x16x32_bf16 v[78:81], v[156:159], v[188:191], v[78:81]
	v_mfma_f32_16x16x32_bf16 v[70:73], v[140:143], v[196:199], v[70:73]
	v_mfma_f32_16x16x32_bf16 v[50:53], v[156:159], v[196:199], v[50:53]
	v_mfma_f32_16x16x32_bf16 v[42:45], v[140:143], v[204:207], v[42:45]
	v_mfma_f32_16x16x32_bf16 v[26:29], v[156:159], v[204:207], v[26:29]
	v_mfma_f32_16x16x32_bf16 v[122:125], v[148:151], v[184:187], v[122:125]
	v_mfma_f32_16x16x32_bf16 v[114:117], v[160:163], v[184:187], v[114:117]
	v_mfma_f32_16x16x32_bf16 v[102:105], v[148:151], v[192:195], v[102:105]
	v_mfma_f32_16x16x32_bf16 v[78:81], v[160:163], v[192:195], v[78:81]
	v_mfma_f32_16x16x32_bf16 v[70:73], v[148:151], v[200:203], v[70:73]
	v_mfma_f32_16x16x32_bf16 v[50:53], v[160:163], v[200:203], v[50:53]
	v_mfma_f32_16x16x32_bf16 v[42:45], v[148:151], v[208:211], v[42:45]
	v_mfma_f32_16x16x32_bf16 v[26:29], v[160:163], v[208:211], v[26:29]
	s_setprio 0
	s_setprio 1
	v_mfma_f32_16x16x32_bf16 v[126:129], v[164:167], v[180:183], v[126:129]
	v_mfma_f32_16x16x32_bf16 v[130:133], v[172:175], v[180:183], v[130:133]
	v_mfma_f32_16x16x32_bf16 v[110:113], v[164:167], v[188:191], v[110:113]
	v_mfma_f32_16x16x32_bf16 v[118:121], v[172:175], v[188:191], v[118:121]
	v_mfma_f32_16x16x32_bf16 v[86:89], v[164:167], v[196:199], v[86:89]
	v_mfma_f32_16x16x32_bf16 v[90:93], v[172:175], v[196:199], v[90:93]
	v_mfma_f32_16x16x32_bf16 v[58:61], v[164:167], v[204:207], v[58:61]
	v_mfma_f32_16x16x32_bf16 v[94:97], v[172:175], v[204:207], v[94:97]
	v_mfma_f32_16x16x32_bf16 v[126:129], v[168:171], v[184:187], v[126:129]
	v_mfma_f32_16x16x32_bf16 v[130:133], v[176:179], v[184:187], v[130:133]
	v_mfma_f32_16x16x32_bf16 v[110:113], v[168:171], v[192:195], v[110:113]
	v_mfma_f32_16x16x32_bf16 v[118:121], v[176:179], v[192:195], v[118:121]
	v_mfma_f32_16x16x32_bf16 v[86:89], v[168:171], v[200:203], v[86:89]
	v_mfma_f32_16x16x32_bf16 v[90:93], v[176:179], v[200:203], v[90:93]
	v_mfma_f32_16x16x32_bf16 v[58:61], v[168:171], v[208:211], v[58:61]
	v_mfma_f32_16x16x32_bf16 v[94:97], v[176:179], v[208:211], v[94:97]
	s_setprio 0
	s_barrier
	s_mov_b64 s[14:15], 0x80
	s_add_i32 s10, s12, s52
	s_add_u32 s62, s0, 0x80
	s_addc_u32 s63, s1, 0
	s_mov_b32 m0, s10
	ds_read_b128 v[180:183], v154 offset:49152
	ds_read_b128 v[184:187], v154 offset:50176
	ds_read_b128 v[188:191], v154 offset:51200
	ds_read_b128 v[192:195], v154 offset:52224
	ds_read_b128 v[196:199], v154 offset:53248
	ds_read_b128 v[200:203], v154 offset:54272
	ds_read_b128 v[204:207], v154 offset:55296
	ds_read_b128 v[208:211], v154 offset:56320
	global_load_lds_dwordx4 v138, s[62:63]
	s_add_i32 m0, s10, 0x2000
	s_add_u32 s0, s0, 0x80080
	s_addc_u32 s1, s1, 0
	s_add_i32 s10, s13, s52
	global_load_lds_dwordx4 v134, s[62:63]
	s_mov_b32 m0, s10
	s_nop 0
	global_load_lds_dwordx4 v138, s[0:1]
	s_add_i32 m0, s10, 0x2000
	s_nop 0
	global_load_lds_dwordx4 v134, s[0:1]
	s_add_u32 s64, s46, 0x80
	s_addc_u32 s65, s47, 0
	s_waitcnt vmcnt(6)
	s_waitcnt lgkmcnt(0)
	s_barrier
	s_setprio 1
	s_waitcnt lgkmcnt(0)
	v_mfma_f32_16x16x32_bf16 v[82:85], v[140:143], v[180:183], v[82:85]
	v_mfma_f32_16x16x32_bf16 v[62:65], v[156:159], v[180:183], v[62:65]
	v_mfma_f32_16x16x32_bf16 v[54:57], v[140:143], v[188:191], v[54:57]
	v_mfma_f32_16x16x32_bf16 v[34:37], v[156:159], v[188:191], v[34:37]
	v_mfma_f32_16x16x32_bf16 v[30:33], v[140:143], v[196:199], v[30:33]
	v_mfma_f32_16x16x32_bf16 v[14:17], v[156:159], v[196:199], v[14:17]
	v_mfma_f32_16x16x32_bf16 v[10:13], v[140:143], v[204:207], v[10:13]
	s_mov_b32 m0, s57
	v_mfma_f32_16x16x32_bf16 v[6:9], v[156:159], v[204:207], v[6:9]
	global_load_lds_dwordx4 v146, s[64:65]
	v_mfma_f32_16x16x32_bf16 v[82:85], v[148:151], v[184:187], v[82:85]
	v_mfma_f32_16x16x32_bf16 v[62:65], v[160:163], v[184:187], v[62:65]
	v_mfma_f32_16x16x32_bf16 v[54:57], v[148:151], v[192:195], v[54:57]
	v_mfma_f32_16x16x32_bf16 v[34:37], v[160:163], v[192:195], v[34:37]
	v_mfma_f32_16x16x32_bf16 v[30:33], v[148:151], v[200:203], v[30:33]
	v_mfma_f32_16x16x32_bf16 v[14:17], v[160:163], v[200:203], v[14:17]
	v_mfma_f32_16x16x32_bf16 v[10:13], v[148:151], v[208:211], v[10:13]
	s_mov_b32 m0, s58
	v_mfma_f32_16x16x32_bf16 v[6:9], v[160:163], v[208:211], v[6:9]
	global_load_lds_dwordx4 v136, s[64:65]
	s_setprio 0
	s_setprio 1
	v_mfma_f32_16x16x32_bf16 v[98:101], v[164:167], v[180:183], v[98:101]
	v_mfma_f32_16x16x32_bf16 v[106:109], v[172:175], v[180:183], v[106:109]
	v_mfma_f32_16x16x32_bf16 v[66:69], v[164:167], v[188:191], v[66:69]
	v_mfma_f32_16x16x32_bf16 v[74:77], v[172:175], v[188:191], v[74:77]
	v_mfma_f32_16x16x32_bf16 v[38:41], v[164:167], v[196:199], v[38:41]
	v_mfma_f32_16x16x32_bf16 v[46:49], v[172:175], v[196:199], v[46:49]
	v_mfma_f32_16x16x32_bf16 v[18:21], v[164:167], v[204:207], v[18:21]
	v_mfma_f32_16x16x32_bf16 v[22:25], v[172:175], v[204:207], v[22:25]
	v_mfma_f32_16x16x32_bf16 v[98:101], v[168:171], v[184:187], v[98:101]
	v_mfma_f32_16x16x32_bf16 v[106:109], v[176:179], v[184:187], v[106:109]
	v_mfma_f32_16x16x32_bf16 v[66:69], v[168:171], v[192:195], v[66:69]
	v_mfma_f32_16x16x32_bf16 v[74:77], v[176:179], v[192:195], v[74:77]
	v_mfma_f32_16x16x32_bf16 v[38:41], v[168:171], v[200:203], v[38:41]
	v_mfma_f32_16x16x32_bf16 v[46:49], v[176:179], v[200:203], v[46:49]
	v_mfma_f32_16x16x32_bf16 v[18:21], v[168:171], v[208:211], v[18:21]
	v_mfma_f32_16x16x32_bf16 v[22:25], v[176:179], v[208:211], v[22:25]
	s_setprio 0
	s_barrier
	s_cmp_gt_u32 s8, 29
	s_cbranch_scc1 .LBB0_350
	s_mov_b32 s8, s9
	s_branch .LBB0_346

.LBB0_625:
	s_add_u32 s13, s0, 0xfffc0080
	s_addc_u32 s14, s1, -1
	s_add_i32 s15, 0, 0x10000
	s_cmp_eq_u32 s12, 12
	s_cselect_b32 s39, s6, s14
	s_cselect_b32 s38, s7, s13
	v_add_u32_e32 v138, s15, v151
	s_cselect_b32 s35, s8, s11
	s_cselect_b32 s34, s9, s10
	s_add_i32 s13, 0, 0x14000
	ds_read_b128 v[164:167], v138
	ds_read_b128 v[168:171], v138 offset:1024
	ds_read_b128 v[172:175], v138 offset:2048
	ds_read_b128 v[176:179], v138 offset:3072
	v_add_u32_e32 v138, s13, v151
	ds_read_b128 v[180:183], v138
	ds_read_b128 v[184:187], v138 offset:1024
	ds_read_b128 v[188:191], v138 offset:2048
	ds_read_b128 v[192:195], v138 offset:3072
	s_add_i32 m0, s59, 0xc000
	ds_read_b128 v[196:199], v162
	ds_read_b128 v[200:203], v162 offset:1024
	ds_read_b128 v[204:207], v162 offset:2048
	ds_read_b128 v[208:211], v162 offset:3072
	ds_read_b128 v[212:215], v162 offset:4096
	ds_read_b128 v[216:219], v162 offset:5120
	ds_read_b128 v[236:239], v162 offset:6144
	ds_read_b128 v[240:243], v162 offset:7168
	global_load_lds_dwordx4 v154, s[0:1]
	s_add_i32 m0, s59, 0xe000
	s_nop 0
	global_load_lds_dwordx4 v156, s[0:1]
	s_waitcnt vmcnt(8)
	s_waitcnt lgkmcnt(0)
	s_barrier
	s_setprio 1
	s_waitcnt lgkmcnt(0)
	v_mfma_f32_16x16x32_bf16 v[130:133], v[164:167], v[196:199], v[130:133]
	v_mfma_f32_16x16x32_bf16 v[126:129], v[172:175], v[196:199], v[126:129]
	v_mfma_f32_16x16x32_bf16 v[114:117], v[164:167], v[204:207], v[114:117]
	v_mfma_f32_16x16x32_bf16 v[110:113], v[172:175], v[204:207], v[110:113]
	v_mfma_f32_16x16x32_bf16 v[98:101], v[164:167], v[212:215], v[98:101]
	v_mfma_f32_16x16x32_bf16 v[94:97], v[172:175], v[212:215], v[94:97]
	v_mfma_f32_16x16x32_bf16 v[82:85], v[164:167], v[236:239], v[82:85]
	v_mfma_f32_16x16x32_bf16 v[78:81], v[172:175], v[236:239], v[78:81]
	v_mfma_f32_16x16x32_bf16 v[130:133], v[168:171], v[200:203], v[130:133]
	v_mfma_f32_16x16x32_bf16 v[126:129], v[176:179], v[200:203], v[126:129]
	v_mfma_f32_16x16x32_bf16 v[114:117], v[168:171], v[208:211], v[114:117]
	v_mfma_f32_16x16x32_bf16 v[110:113], v[176:179], v[208:211], v[110:113]
	v_mfma_f32_16x16x32_bf16 v[98:101], v[168:171], v[216:219], v[98:101]
	v_mfma_f32_16x16x32_bf16 v[94:97], v[176:179], v[216:219], v[94:97]
	v_mfma_f32_16x16x32_bf16 v[82:85], v[168:171], v[240:243], v[82:85]
	v_mfma_f32_16x16x32_bf16 v[78:81], v[176:179], v[240:243], v[78:81]
	s_setprio 0
	s_setprio 1
	v_mfma_f32_16x16x32_bf16 v[122:125], v[180:183], v[196:199], v[122:125]
	v_mfma_f32_16x16x32_bf16 v[118:121], v[188:191], v[196:199], v[118:121]
	v_mfma_f32_16x16x32_bf16 v[106:109], v[180:183], v[204:207], v[106:109]
	v_mfma_f32_16x16x32_bf16 v[102:105], v[188:191], v[204:207], v[102:105]
	v_mfma_f32_16x16x32_bf16 v[90:93], v[180:183], v[212:215], v[90:93]
	v_mfma_f32_16x16x32_bf16 v[86:89], v[188:191], v[212:215], v[86:89]
	v_mfma_f32_16x16x32_bf16 v[74:77], v[180:183], v[236:239], v[74:77]
	v_mfma_f32_16x16x32_bf16 v[70:73], v[188:191], v[236:239], v[70:73]
	v_mfma_f32_16x16x32_bf16 v[122:125], v[184:187], v[200:203], v[122:125]
	v_mfma_f32_16x16x32_bf16 v[118:121], v[192:195], v[200:203], v[118:121]
	v_mfma_f32_16x16x32_bf16 v[106:109], v[184:187], v[208:211], v[106:109]
	v_mfma_f32_16x16x32_bf16 v[102:105], v[192:195], v[208:211], v[102:105]
	v_mfma_f32_16x16x32_bf16 v[90:93], v[184:187], v[216:219], v[90:93]
	v_mfma_f32_16x16x32_bf16 v[86:89], v[192:195], v[216:219], v[86:89]
	v_mfma_f32_16x16x32_bf16 v[74:77], v[184:187], v[240:243], v[74:77]
	v_mfma_f32_16x16x32_bf16 v[70:73], v[192:195], v[240:243], v[70:73]
	s_setprio 0
	s_barrier
	s_add_i32 s14, s15, s56
	s_mov_b32 m0, s14
	ds_read_b128 v[196:199], v162 offset:16384
	ds_read_b128 v[200:203], v162 offset:17408
	ds_read_b128 v[204:207], v162 offset:18432
	ds_read_b128 v[208:211], v162 offset:19456
	ds_read_b128 v[212:215], v162 offset:20480
	ds_read_b128 v[216:219], v162 offset:21504
	ds_read_b128 v[236:239], v162 offset:22528
	ds_read_b128 v[240:243], v162 offset:23552
	global_load_lds_dwordx4 v146, s[34:35]
	s_add_i32 m0, s14, 0x2000
	s_add_u32 s14, s34, 0x40000
	s_addc_u32 s15, s35, 0
	s_add_i32 s13, s13, s56
	global_load_lds_dwordx4 v134, s[34:35]
	s_mov_b32 m0, s13
	s_nop 0
	global_load_lds_dwordx4 v146, s[14:15]
	s_add_i32 m0, s13, 0x2000
	s_nop 0
	global_load_lds_dwordx4 v134, s[14:15]
	s_waitcnt vmcnt(6)
	s_waitcnt lgkmcnt(0)
	s_barrier
	s_setprio 1
	s_waitcnt lgkmcnt(0)
	v_mfma_f32_16x16x32_bf16 v[66:69], v[164:167], v[196:199], v[66:69]
	v_mfma_f32_16x16x32_bf16 v[62:65], v[172:175], v[196:199], v[62:65]
	v_mfma_f32_16x16x32_bf16 v[50:53], v[164:167], v[204:207], v[50:53]
	v_mfma_f32_16x16x32_bf16 v[46:49], v[172:175], v[204:207], v[46:49]
	v_mfma_f32_16x16x32_bf16 v[34:37], v[164:167], v[212:215], v[34:37]
	v_mfma_f32_16x16x32_bf16 v[30:33], v[172:175], v[212:215], v[30:33]
	v_mfma_f32_16x16x32_bf16 v[18:21], v[164:167], v[236:239], v[18:21]
	s_mov_b32 m0, s59
	v_mfma_f32_16x16x32_bf16 v[14:17], v[172:175], v[236:239], v[14:17]
	global_load_lds_dwordx4 v148, s[38:39]
	v_mfma_f32_16x16x32_bf16 v[66:69], v[168:171], v[200:203], v[66:69]
	v_mfma_f32_16x16x32_bf16 v[62:65], v[176:179], v[200:203], v[62:65]
	v_mfma_f32_16x16x32_bf16 v[50:53], v[168:171], v[208:211], v[50:53]
	v_mfma_f32_16x16x32_bf16 v[46:49], v[176:179], v[208:211], v[46:49]
	v_mfma_f32_16x16x32_bf16 v[34:37], v[168:171], v[216:219], v[34:37]
	v_mfma_f32_16x16x32_bf16 v[30:33], v[176:179], v[216:219], v[30:33]
	v_mfma_f32_16x16x32_bf16 v[18:21], v[168:171], v[240:243], v[18:21]
	s_mov_b32 m0, s60
	v_mfma_f32_16x16x32_bf16 v[14:17], v[176:179], v[240:243], v[14:17]
	global_load_lds_dwordx4 v136, s[38:39]
	s_setprio 0
	s_setprio 1
	v_mfma_f32_16x16x32_bf16 v[58:61], v[180:183], v[196:199], v[58:61]
	v_mfma_f32_16x16x32_bf16 v[54:57], v[188:191], v[196:199], v[54:57]
	v_mfma_f32_16x16x32_bf16 v[42:45], v[180:183], v[204:207], v[42:45]
	v_mfma_f32_16x16x32_bf16 v[38:41], v[188:191], v[204:207], v[38:41]
	v_mfma_f32_16x16x32_bf16 v[26:29], v[180:183], v[212:215], v[26:29]
	v_mfma_f32_16x16x32_bf16 v[22:25], v[188:191], v[212:215], v[22:25]
	v_mfma_f32_16x16x32_bf16 v[10:13], v[180:183], v[236:239], v[10:13]
	v_mfma_f32_16x16x32_bf16 v[6:9], v[188:191], v[236:239], v[6:9]
	v_mfma_f32_16x16x32_bf16 v[58:61], v[184:187], v[200:203], v[58:61]
	v_mfma_f32_16x16x32_bf16 v[54:57], v[192:195], v[200:203], v[54:57]
	v_mfma_f32_16x16x32_bf16 v[42:45], v[184:187], v[208:211], v[42:45]
	v_mfma_f32_16x16x32_bf16 v[38:41], v[192:195], v[208:211], v[38:41]
	v_mfma_f32_16x16x32_bf16 v[26:29], v[184:187], v[216:219], v[26:29]
	v_mfma_f32_16x16x32_bf16 v[22:25], v[192:195], v[216:219], v[22:25]
	v_mfma_f32_16x16x32_bf16 v[10:13], v[184:187], v[240:243], v[10:13]
	v_mfma_f32_16x16x32_bf16 v[6:9], v[192:195], v[240:243], v[6:9]
	s_setprio 0
	s_barrier
	s_add_i32 s13, 0, 0x18000
	v_add_u32_e32 v138, s13, v151
	s_add_i32 s16, 0, 0x1c000
	ds_read_b128 v[164:167], v138
	ds_read_b128 v[168:171], v138 offset:1024
	ds_read_b128 v[172:175], v138 offset:2048
	ds_read_b128 v[176:179], v138 offset:3072
	v_add_u32_e32 v138, s16, v151
	ds_read_b128 v[180:183], v138
	ds_read_b128 v[184:187], v138 offset:1024
	ds_read_b128 v[188:191], v138 offset:2048
	ds_read_b128 v[192:195], v138 offset:3072
	s_add_u32 s14, s38, 0x40000
	s_addc_u32 s15, s39, 0
	s_mov_b32 m0, s61
	ds_read_b128 v[196:199], v162 offset:32768
	ds_read_b128 v[200:203], v162 offset:33792
	ds_read_b128 v[204:207], v162 offset:34816
	ds_read_b128 v[208:211], v162 offset:35840
	ds_read_b128 v[212:215], v162 offset:36864
	ds_read_b128 v[216:219], v162 offset:37888
	ds_read_b128 v[236:239], v162 offset:38912
	ds_read_b128 v[240:243], v162 offset:39936
	global_load_lds_dwordx4 v148, s[14:15]
	s_mov_b32 m0, s62
	s_nop 0
	global_load_lds_dwordx4 v136, s[14:15]
	s_waitcnt vmcnt(8)
	s_waitcnt lgkmcnt(0)
	s_barrier
	s_setprio 1
	s_waitcnt lgkmcnt(0)
	v_mfma_f32_16x16x32_bf16 v[130:133], v[164:167], v[196:199], v[130:133]
	v_mfma_f32_16x16x32_bf16 v[126:129], v[172:175], v[196:199], v[126:129]
	v_mfma_f32_16x16x32_bf16 v[114:117], v[164:167], v[204:207], v[114:117]
	v_mfma_f32_16x16x32_bf16 v[110:113], v[172:175], v[204:207], v[110:113]
	v_mfma_f32_16x16x32_bf16 v[98:101], v[164:167], v[212:215], v[98:101]
	v_mfma_f32_16x16x32_bf16 v[94:97], v[172:175], v[212:215], v[94:97]
	v_mfma_f32_16x16x32_bf16 v[82:85], v[164:167], v[236:239], v[82:85]
	v_mfma_f32_16x16x32_bf16 v[78:81], v[172:175], v[236:239], v[78:81]
	v_mfma_f32_16x16x32_bf16 v[130:133], v[168:171], v[200:203], v[130:133]
	v_mfma_f32_16x16x32_bf16 v[126:129], v[176:179], v[200:203], v[126:129]
	v_mfma_f32_16x16x32_bf16 v[114:117], v[168:171], v[208:211], v[114:117]
	v_mfma_f32_16x16x32_bf16 v[110:113], v[176:179], v[208:211], v[110:113]
	v_mfma_f32_16x16x32_bf16 v[98:101], v[168:171], v[216:219], v[98:101]
	v_mfma_f32_16x16x32_bf16 v[94:97], v[176:179], v[216:219], v[94:97]
	v_mfma_f32_16x16x32_bf16 v[82:85], v[168:171], v[240:243], v[82:85]
	v_mfma_f32_16x16x32_bf16 v[78:81], v[176:179], v[240:243], v[78:81]
	s_setprio 0
	s_setprio 1
	v_mfma_f32_16x16x32_bf16 v[122:125], v[180:183], v[196:199], v[122:125]
	v_mfma_f32_16x16x32_bf16 v[118:121], v[188:191], v[196:199], v[118:121]
	v_mfma_f32_16x16x32_bf16 v[106:109], v[180:183], v[204:207], v[106:109]
	v_mfma_f32_16x16x32_bf16 v[102:105], v[188:191], v[204:207], v[102:105]
	v_mfma_f32_16x16x32_bf16 v[90:93], v[180:183], v[212:215], v[90:93]
	v_mfma_f32_16x16x32_bf16 v[86:89], v[188:191], v[212:215], v[86:89]
	v_mfma_f32_16x16x32_bf16 v[74:77], v[180:183], v[236:239], v[74:77]
	v_mfma_f32_16x16x32_bf16 v[70:73], v[188:191], v[236:239], v[70:73]
	v_mfma_f32_16x16x32_bf16 v[122:125], v[184:187], v[200:203], v[122:125]
	v_mfma_f32_16x16x32_bf16 v[118:121], v[192:195], v[200:203], v[118:121]
	v_mfma_f32_16x16x32_bf16 v[106:109], v[184:187], v[208:211], v[106:109]
	v_mfma_f32_16x16x32_bf16 v[102:105], v[192:195], v[208:211], v[102:105]
	v_mfma_f32_16x16x32_bf16 v[90:93], v[184:187], v[216:219], v[90:93]
	v_mfma_f32_16x16x32_bf16 v[86:89], v[192:195], v[216:219], v[86:89]
	v_mfma_f32_16x16x32_bf16 v[74:77], v[184:187], v[240:243], v[74:77]
	v_mfma_f32_16x16x32_bf16 v[70:73], v[192:195], v[240:243], v[70:73]
	s_setprio 0
	s_barrier
	s_add_i32 s13, s13, s56
	s_add_u32 s42, s34, 0x80
	s_addc_u32 s43, s35, 0
	s_mov_b32 m0, s13
	ds_read_b128 v[196:199], v162 offset:49152
	ds_read_b128 v[200:203], v162 offset:50176
	ds_read_b128 v[204:207], v162 offset:51200
	ds_read_b128 v[208:211], v162 offset:52224
	ds_read_b128 v[212:215], v162 offset:53248
	ds_read_b128 v[216:219], v162 offset:54272
	ds_read_b128 v[236:239], v162 offset:55296
	ds_read_b128 v[240:243], v162 offset:56320
	global_load_lds_dwordx4 v146, s[42:43]
	s_add_i32 m0, s13, 0x2000
	s_add_u32 s14, s34, 0x40080
	s_addc_u32 s15, s35, 0
	s_add_i32 s13, s16, s56
	global_load_lds_dwordx4 v134, s[42:43]
	s_mov_b32 m0, s13
	s_nop 0
	global_load_lds_dwordx4 v146, s[14:15]
	s_add_i32 m0, s13, 0x2000
	s_nop 0
	global_load_lds_dwordx4 v134, s[14:15]
	s_add_u32 s50, s38, 0x80
	s_addc_u32 s51, s39, 0
	s_waitcnt vmcnt(6)
	s_waitcnt lgkmcnt(0)
	s_barrier
	s_setprio 1
	s_waitcnt lgkmcnt(0)
	v_mfma_f32_16x16x32_bf16 v[66:69], v[164:167], v[196:199], v[66:69]
	v_mfma_f32_16x16x32_bf16 v[62:65], v[172:175], v[196:199], v[62:65]
	v_mfma_f32_16x16x32_bf16 v[50:53], v[164:167], v[204:207], v[50:53]
	v_mfma_f32_16x16x32_bf16 v[46:49], v[172:175], v[204:207], v[46:49]
	v_mfma_f32_16x16x32_bf16 v[34:37], v[164:167], v[212:215], v[34:37]
	v_mfma_f32_16x16x32_bf16 v[30:33], v[172:175], v[212:215], v[30:33]
	v_mfma_f32_16x16x32_bf16 v[18:21], v[164:167], v[236:239], v[18:21]
	s_mov_b32 m0, s64
	v_mfma_f32_16x16x32_bf16 v[14:17], v[172:175], v[236:239], v[14:17]
	global_load_lds_dwordx4 v148, s[50:51]
	v_mfma_f32_16x16x32_bf16 v[66:69], v[168:171], v[200:203], v[66:69]
	v_mfma_f32_16x16x32_bf16 v[62:65], v[176:179], v[200:203], v[62:65]
	v_mfma_f32_16x16x32_bf16 v[50:53], v[168:171], v[208:211], v[50:53]
	v_mfma_f32_16x16x32_bf16 v[46:49], v[176:179], v[208:211], v[46:49]
	v_mfma_f32_16x16x32_bf16 v[34:37], v[168:171], v[216:219], v[34:37]
	v_mfma_f32_16x16x32_bf16 v[30:33], v[176:179], v[216:219], v[30:33]
	v_mfma_f32_16x16x32_bf16 v[18:21], v[168:171], v[240:243], v[18:21]
	s_mov_b32 m0, s65
	v_mfma_f32_16x16x32_bf16 v[14:17], v[176:179], v[240:243], v[14:17]
	global_load_lds_dwordx4 v136, s[50:51]
	s_setprio 0
	s_setprio 1
	v_mfma_f32_16x16x32_bf16 v[58:61], v[180:183], v[196:199], v[58:61]
	v_mfma_f32_16x16x32_bf16 v[54:57], v[188:191], v[196:199], v[54:57]
	v_mfma_f32_16x16x32_bf16 v[42:45], v[180:183], v[204:207], v[42:45]
	v_mfma_f32_16x16x32_bf16 v[38:41], v[188:191], v[204:207], v[38:41]
	v_mfma_f32_16x16x32_bf16 v[26:29], v[180:183], v[212:215], v[26:29]
	v_mfma_f32_16x16x32_bf16 v[22:25], v[188:191], v[212:215], v[22:25]
	v_mfma_f32_16x16x32_bf16 v[10:13], v[180:183], v[236:239], v[10:13]
	v_mfma_f32_16x16x32_bf16 v[6:9], v[188:191], v[236:239], v[6:9]
	v_mfma_f32_16x16x32_bf16 v[58:61], v[184:187], v[200:203], v[58:61]
	v_mfma_f32_16x16x32_bf16 v[54:57], v[192:195], v[200:203], v[54:57]
	v_mfma_f32_16x16x32_bf16 v[42:45], v[184:187], v[208:211], v[42:45]
	v_mfma_f32_16x16x32_bf16 v[38:41], v[192:195], v[208:211], v[38:41]
	v_mfma_f32_16x16x32_bf16 v[26:29], v[184:187], v[216:219], v[26:29]
	v_mfma_f32_16x16x32_bf16 v[22:25], v[192:195], v[216:219], v[22:25]
	v_mfma_f32_16x16x32_bf16 v[10:13], v[184:187], v[240:243], v[10:13]
	v_mfma_f32_16x16x32_bf16 v[6:9], v[192:195], v[240:243], v[6:9]
	s_setprio 0
	s_barrier
	s_add_i32 s12, s12, 2
	s_add_u32 s0, s0, 0x100
	s_addc_u32 s1, s1, 0
	s_add_u32 s10, s10, 0x100
	s_addc_u32 s11, s11, 0
	s_cmp_gt_u32 s12, 13
	s_cbranch_scc0 .LBB0_625
	s_and_b64 vcc, exec, s[24:25]
	s_cbranch_vccz .LBB0_628
	s_barrier
